# prompt attention (FoX and MLA) pass ends: the O stores are no longer drained with vmcnt(0) before the pass barrier; they complete under the next pass's loads (on top of v25)
# baseline (speedup 1.0000x reference)
.LBB0_710:
	v_lshlrev_b64 v[74:75], 1, v[134:135]
	v_lshl_add_u64 v[2:3], s[76:77], 0, v[74:75]
	v_lshlrev_b32_e32 v70, 1, v1
	v_mov_b32_e32 v71, v4
	v_lshl_add_u64 v[2:3], v[2:3], 0, v[70:71]
	global_load_dwordx2 v[96:97], v[2:3], off
	global_load_dwordx2 v[98:99], v[2:3], off offset:16
	global_load_dwordx2 v[100:101], v[2:3], off offset:32
	global_load_dwordx2 v[94:95], v[2:3], off offset:48
	global_load_dwordx2 v[92:93], v[2:3], off offset:64
	global_load_dwordx2 v[90:91], v[2:3], off offset:80
	global_load_dwordx2 v[88:89], v[2:3], off offset:96
	global_load_dwordx2 v[86:87], v[2:3], off offset:112
	global_load_dwordx2 v[84:85], v[2:3], off offset:128
	global_load_dwordx2 v[82:83], v[2:3], off offset:144
	global_load_dwordx2 v[80:81], v[2:3], off offset:160
	global_load_dwordx2 v[78:79], v[2:3], off offset:176
	global_load_dwordx2 v[76:77], v[2:3], off offset:192
	global_load_dwordx2 v[72:73], v[2:3], off offset:208
	global_load_dwordx2 v[70:71], v[2:3], off offset:224
	s_nop 0
	global_load_dwordx2 v[2:3], v[2:3], off offset:240
	v_rcp_f32_e32 v1, v158
	v_lshl_add_u64 v[74:75], s[78:79], 0, v[74:75]
	v_lshlrev_b32_e32 v102, 1, v136
	v_mov_b32_e32 v103, v4
	v_mul_f32_e32 v54, v54, v1
	v_lshl_add_u64 v[74:75], v[74:75], 0, v[102:103]
	v_mul_f32_e32 v58, v58, v1
	v_mul_f32_e32 v38, v38, v1
	v_mul_f32_e32 v42, v42, v1
	v_mul_f32_e32 v22, v22, v1
	v_mul_f32_e32 v26, v26, v1
	v_mul_f32_e32 v6, v6, v1
	v_mul_f32_e32 v10, v10, v1
	s_mov_b64 s[0:1], 0
	s_and_b64 vcc, exec, s[80:81]
	s_movk_i32 s89, 0x60
	s_waitcnt vmcnt(0)
	v_lshlrev_b32_e32 v5, 16, v96
	v_and_b32_e32 v96, 0xffff0000, v96
	v_mul_f32_e32 v5, v54, v5
	v_mul_f32_e32 v54, v55, v1
	v_mul_f32_e32 v54, v54, v96
	v_lshlrev_b32_e32 v102, 16, v97
	v_and_b32_e32 v97, 0xffff0000, v97
	v_cvt_pk_bf16_f32 v54, v5, v54
	v_mul_f32_e32 v5, v56, v1
	v_mul_f32_e32 v55, v57, v1
	v_mul_f32_e32 v5, v5, v102
	v_mul_f32_e32 v55, v55, v97
	v_cvt_pk_bf16_f32 v55, v5, v55
	v_lshlrev_b32_e32 v5, 16, v98
	v_and_b32_e32 v56, 0xffff0000, v98
	v_mul_f32_e32 v5, v58, v5
	v_mul_f32_e32 v58, v59, v1
	v_mul_f32_e32 v56, v58, v56
	v_lshlrev_b32_e32 v57, 16, v99
	v_cvt_pk_bf16_f32 v56, v5, v56
	v_mul_f32_e32 v5, v60, v1
	v_and_b32_e32 v96, 0xffff0000, v99
	v_mul_f32_e32 v5, v5, v57
	v_mul_f32_e32 v57, v61, v1
	v_mul_f32_e32 v57, v57, v96
	v_cvt_pk_bf16_f32 v57, v5, v57
	v_permlane32_swap_b32_e32 v54, v56
	s_nop 0
	v_permlane32_swap_b32_e32 v55, v57
	global_store_dwordx4 v[74:75], v[54:57], off
	v_lshlrev_b32_e32 v5, 16, v100
	v_mul_f32_e32 v59, v66, v1
	v_mul_f32_e32 v57, v62, v1
	v_and_b32_e32 v54, 0xffff0000, v100
	v_mul_f32_e32 v5, v57, v5
	v_mul_f32_e32 v57, v63, v1
	v_mul_f32_e32 v54, v57, v54
	v_lshlrev_b32_e32 v55, 16, v101
	v_cvt_pk_bf16_f32 v54, v5, v54
	v_mul_f32_e32 v5, v64, v1
	v_and_b32_e32 v56, 0xffff0000, v101
	v_mul_f32_e32 v5, v5, v55
	v_mul_f32_e32 v55, v65, v1
	v_mul_f32_e32 v55, v55, v56
	v_cvt_pk_bf16_f32 v55, v5, v55
	v_lshlrev_b32_e32 v5, 16, v94
	v_and_b32_e32 v56, 0xffff0000, v94
	v_mul_f32_e32 v5, v59, v5
	v_mul_f32_e32 v59, v67, v1
	v_mul_f32_e32 v56, v59, v56
	v_lshlrev_b32_e32 v57, 16, v95
	v_cvt_pk_bf16_f32 v56, v5, v56
	v_mul_f32_e32 v5, v68, v1
	v_and_b32_e32 v58, 0xffff0000, v95
	v_mul_f32_e32 v5, v5, v57
	v_mul_f32_e32 v57, v69, v1
	v_mul_f32_e32 v57, v57, v58
	v_cvt_pk_bf16_f32 v57, v5, v57
	v_permlane32_swap_b32_e32 v54, v56
	s_nop 0
	v_permlane32_swap_b32_e32 v55, v57
	v_lshlrev_b32_e32 v5, 16, v92
	global_store_dwordx4 v[74:75], v[54:57], off offset:32
	v_mul_f32_e32 v5, v38, v5
	v_mul_f32_e32 v38, v39, v1
	v_and_b32_e32 v54, 0xffff0000, v92
	v_mul_f32_e32 v38, v38, v54
	v_lshlrev_b32_e32 v55, 16, v93
	v_and_b32_e32 v56, 0xffff0000, v93
	v_cvt_pk_bf16_f32 v38, v5, v38
	v_mul_f32_e32 v5, v40, v1
	v_mul_f32_e32 v39, v41, v1
	v_mul_f32_e32 v5, v5, v55
	v_mul_f32_e32 v39, v39, v56
	v_cvt_pk_bf16_f32 v39, v5, v39
	v_lshlrev_b32_e32 v5, 16, v90
	v_and_b32_e32 v40, 0xffff0000, v90
	v_mul_f32_e32 v5, v42, v5
	v_mul_f32_e32 v42, v43, v1
	v_mul_f32_e32 v40, v42, v40
	v_lshlrev_b32_e32 v41, 16, v91
	v_cvt_pk_bf16_f32 v40, v5, v40
	v_mul_f32_e32 v5, v44, v1
	v_and_b32_e32 v54, 0xffff0000, v91
	v_mul_f32_e32 v5, v5, v41
	v_mul_f32_e32 v41, v45, v1
	v_mul_f32_e32 v41, v41, v54
	v_cvt_pk_bf16_f32 v41, v5, v41
	v_permlane32_swap_b32_e32 v38, v40
	s_nop 0
	v_permlane32_swap_b32_e32 v39, v41
	global_store_dwordx4 v[74:75], v[38:41], off offset:64
	v_lshlrev_b32_e32 v5, 16, v88
	v_mul_f32_e32 v43, v50, v1
	v_mul_f32_e32 v41, v46, v1
	v_and_b32_e32 v38, 0xffff0000, v88
	v_mul_f32_e32 v5, v41, v5
	v_mul_f32_e32 v41, v47, v1
	v_mul_f32_e32 v38, v41, v38
	v_lshlrev_b32_e32 v39, 16, v89
	v_cvt_pk_bf16_f32 v38, v5, v38
	v_mul_f32_e32 v5, v48, v1
	v_and_b32_e32 v40, 0xffff0000, v89
	v_mul_f32_e32 v5, v5, v39
	v_mul_f32_e32 v39, v49, v1
	v_mul_f32_e32 v39, v39, v40
	v_cvt_pk_bf16_f32 v39, v5, v39
	v_lshlrev_b32_e32 v5, 16, v86
	v_and_b32_e32 v40, 0xffff0000, v86
	v_mul_f32_e32 v5, v43, v5
	v_mul_f32_e32 v43, v51, v1
	v_mul_f32_e32 v40, v43, v40
	v_lshlrev_b32_e32 v41, 16, v87
	v_cvt_pk_bf16_f32 v40, v5, v40
	v_mul_f32_e32 v5, v52, v1
	v_and_b32_e32 v42, 0xffff0000, v87
	v_mul_f32_e32 v5, v5, v41
	v_mul_f32_e32 v41, v53, v1
	v_mul_f32_e32 v41, v41, v42
	v_cvt_pk_bf16_f32 v41, v5, v41
	v_permlane32_swap_b32_e32 v38, v40
	s_nop 0
	v_permlane32_swap_b32_e32 v39, v41
	v_lshlrev_b32_e32 v5, 16, v84
	global_store_dwordx4 v[74:75], v[38:41], off offset:96
	v_mul_f32_e32 v5, v22, v5
	v_mul_f32_e32 v22, v23, v1
	v_and_b32_e32 v38, 0xffff0000, v84
	v_mul_f32_e32 v22, v22, v38
	v_lshlrev_b32_e32 v39, 16, v85
	v_and_b32_e32 v40, 0xffff0000, v85
	v_cvt_pk_bf16_f32 v22, v5, v22
	v_mul_f32_e32 v5, v24, v1
	v_mul_f32_e32 v23, v25, v1
	v_mul_f32_e32 v5, v5, v39
	v_mul_f32_e32 v23, v23, v40
	v_cvt_pk_bf16_f32 v23, v5, v23
	v_lshlrev_b32_e32 v5, 16, v82
	v_and_b32_e32 v24, 0xffff0000, v82
	v_mul_f32_e32 v5, v26, v5
	v_mul_f32_e32 v26, v27, v1
	v_mul_f32_e32 v24, v26, v24
	v_lshlrev_b32_e32 v25, 16, v83
	v_cvt_pk_bf16_f32 v24, v5, v24
	v_mul_f32_e32 v5, v28, v1
	v_and_b32_e32 v38, 0xffff0000, v83
	v_mul_f32_e32 v5, v5, v25
	v_mul_f32_e32 v25, v29, v1
	v_mul_f32_e32 v25, v25, v38
	v_cvt_pk_bf16_f32 v25, v5, v25
	v_permlane32_swap_b32_e32 v22, v24
	s_nop 0
	v_permlane32_swap_b32_e32 v23, v25
	global_store_dwordx4 v[74:75], v[22:25], off offset:128
	v_lshlrev_b32_e32 v5, 16, v80
	v_mul_f32_e32 v27, v34, v1
	v_mul_f32_e32 v25, v30, v1
	v_and_b32_e32 v22, 0xffff0000, v80
	v_mul_f32_e32 v5, v25, v5
	v_mul_f32_e32 v25, v31, v1
	v_mul_f32_e32 v22, v25, v22
	v_lshlrev_b32_e32 v23, 16, v81
	v_cvt_pk_bf16_f32 v22, v5, v22
	v_mul_f32_e32 v5, v32, v1
	v_and_b32_e32 v24, 0xffff0000, v81
	v_mul_f32_e32 v5, v5, v23
	v_mul_f32_e32 v23, v33, v1
	v_mul_f32_e32 v23, v23, v24
	v_cvt_pk_bf16_f32 v23, v5, v23
	v_lshlrev_b32_e32 v5, 16, v78
	v_and_b32_e32 v24, 0xffff0000, v78
	v_mul_f32_e32 v5, v27, v5
	v_mul_f32_e32 v27, v35, v1
	v_mul_f32_e32 v24, v27, v24
	v_lshlrev_b32_e32 v25, 16, v79
	v_cvt_pk_bf16_f32 v24, v5, v24
	v_mul_f32_e32 v5, v36, v1
	v_and_b32_e32 v26, 0xffff0000, v79
	v_mul_f32_e32 v5, v5, v25
	v_mul_f32_e32 v25, v37, v1
	v_mul_f32_e32 v25, v25, v26
	v_cvt_pk_bf16_f32 v25, v5, v25
	v_permlane32_swap_b32_e32 v22, v24
	s_nop 0
	v_permlane32_swap_b32_e32 v23, v25
	v_lshlrev_b32_e32 v5, 16, v76
	global_store_dwordx4 v[74:75], v[22:25], off offset:160
	v_mul_f32_e32 v5, v6, v5
	v_mul_f32_e32 v6, v7, v1
	v_and_b32_e32 v22, 0xffff0000, v76
	v_mul_f32_e32 v6, v6, v22
	v_lshlrev_b32_e32 v23, 16, v77
	v_and_b32_e32 v24, 0xffff0000, v77
	v_cvt_pk_bf16_f32 v6, v5, v6
	v_mul_f32_e32 v5, v8, v1
	v_mul_f32_e32 v7, v9, v1
	v_mul_f32_e32 v5, v5, v23
	v_mul_f32_e32 v7, v7, v24
	v_cvt_pk_bf16_f32 v7, v5, v7
	v_lshlrev_b32_e32 v5, 16, v72
	v_and_b32_e32 v8, 0xffff0000, v72
	v_mul_f32_e32 v5, v10, v5
	v_mul_f32_e32 v10, v11, v1
	v_mul_f32_e32 v8, v10, v8
	v_lshlrev_b32_e32 v9, 16, v73
	v_cvt_pk_bf16_f32 v8, v5, v8
	v_mul_f32_e32 v5, v12, v1
	v_and_b32_e32 v22, 0xffff0000, v73
	v_mul_f32_e32 v5, v5, v9
	v_mul_f32_e32 v9, v13, v1
	v_mul_f32_e32 v9, v9, v22
	v_cvt_pk_bf16_f32 v9, v5, v9
	v_permlane32_swap_b32_e32 v6, v8
	s_nop 0
	v_permlane32_swap_b32_e32 v7, v9
	global_store_dwordx4 v[74:75], v[6:9], off offset:192
	v_lshlrev_b32_e32 v5, 16, v70
	s_nop 0
	v_mul_f32_e32 v9, v14, v1
	v_and_b32_e32 v6, 0xffff0000, v70
	v_mul_f32_e32 v5, v9, v5
	v_mul_f32_e32 v9, v15, v1
	v_mul_f32_e32 v6, v9, v6
	v_lshlrev_b32_e32 v7, 16, v71
	v_cvt_pk_bf16_f32 v6, v5, v6
	v_mul_f32_e32 v5, v16, v1
	v_and_b32_e32 v8, 0xffff0000, v71
	v_mul_f32_e32 v5, v5, v7
	v_mul_f32_e32 v7, v17, v1
	v_mul_f32_e32 v7, v7, v8
	v_cvt_pk_bf16_f32 v7, v5, v7
	v_lshlrev_b32_e32 v5, 16, v2
	v_mul_f32_e32 v8, v18, v1
	v_and_b32_e32 v2, 0xffff0000, v2
	v_mul_f32_e32 v5, v8, v5
	v_mul_f32_e32 v8, v19, v1
	v_mul_f32_e32 v2, v8, v2
	v_lshlrev_b32_e32 v9, 16, v3
	v_and_b32_e32 v3, 0xffff0000, v3
	v_cvt_pk_bf16_f32 v8, v5, v2
	v_mul_f32_e32 v2, v20, v1
	v_mul_f32_e32 v1, v21, v1
	v_mul_f32_e32 v2, v2, v9
	v_mul_f32_e32 v1, v1, v3
	v_cvt_pk_bf16_f32 v9, v2, v1
	v_permlane32_swap_b32_e32 v6, v8
	v_permlane32_swap_b32_e32 v7, v9
	global_store_dwordx4 v[74:75], v[6:9], off offset:224
	s_waitcnt lgkmcnt(0)
	s_barrier
	s_cbranch_vccnz .LBB0_726

.LBB0_727:
	v_lshlrev_b64 v[74:75], 13, v[150:151]
	v_lshl_add_u64 v[2:3], s[10:11], 0, v[74:75]
	v_mov_b32_e32 v159, v4
	v_lshl_add_u64 v[2:3], v[2:3], 0, v[158:159]
	global_load_dwordx2 v[96:97], v[2:3], off
	global_load_dwordx2 v[98:99], v[2:3], off offset:16
	global_load_dwordx2 v[100:101], v[2:3], off offset:32
	global_load_dwordx2 v[94:95], v[2:3], off offset:48
	global_load_dwordx2 v[92:93], v[2:3], off offset:64
	global_load_dwordx2 v[90:91], v[2:3], off offset:80
	global_load_dwordx2 v[88:89], v[2:3], off offset:96
	global_load_dwordx2 v[86:87], v[2:3], off offset:112
	global_load_dwordx2 v[84:85], v[2:3], off offset:128
	global_load_dwordx2 v[82:83], v[2:3], off offset:144
	global_load_dwordx2 v[80:81], v[2:3], off offset:160
	global_load_dwordx2 v[78:79], v[2:3], off offset:176
	global_load_dwordx2 v[76:77], v[2:3], off offset:192
	global_load_dwordx2 v[72:73], v[2:3], off offset:208
	global_load_dwordx2 v[70:71], v[2:3], off offset:224
	s_nop 0
	global_load_dwordx2 v[2:3], v[2:3], off offset:240
	v_rcp_f32_e32 v1, v183
	v_lshl_add_u64 v[74:75], s[12:13], 0, v[74:75]
	v_lshlrev_b32_e32 v102, 1, v158
	v_mov_b32_e32 v103, v4
	v_mul_f32_e32 v54, v54, v1
	v_lshl_add_u64 v[74:75], v[74:75], 0, v[102:103]
	v_mul_f32_e32 v58, v58, v1
	v_mul_f32_e32 v38, v38, v1
	v_mul_f32_e32 v42, v42, v1
	v_mul_f32_e32 v22, v22, v1
	v_mul_f32_e32 v26, v26, v1
	v_mul_f32_e32 v6, v6, v1
	v_mul_f32_e32 v10, v10, v1
	s_mov_b64 s[16:17], 0
	s_and_b64 vcc, exec, s[14:15]
	s_waitcnt vmcnt(0)
	v_lshlrev_b32_e32 v5, 16, v96
	v_and_b32_e32 v96, 0xffff0000, v96
	v_mul_f32_e32 v5, v54, v5
	v_mul_f32_e32 v54, v55, v1
	v_mul_f32_e32 v54, v54, v96
	v_lshlrev_b32_e32 v102, 16, v97
	v_and_b32_e32 v97, 0xffff0000, v97
	v_cvt_pk_bf16_f32 v54, v5, v54
	v_mul_f32_e32 v5, v56, v1
	v_mul_f32_e32 v55, v57, v1
	v_mul_f32_e32 v5, v5, v102
	v_mul_f32_e32 v55, v55, v97
	v_cvt_pk_bf16_f32 v55, v5, v55
	v_lshlrev_b32_e32 v5, 16, v98
	v_and_b32_e32 v56, 0xffff0000, v98
	v_mul_f32_e32 v5, v58, v5
	v_mul_f32_e32 v58, v59, v1
	v_mul_f32_e32 v56, v58, v56
	v_lshlrev_b32_e32 v57, 16, v99
	v_cvt_pk_bf16_f32 v56, v5, v56
	v_mul_f32_e32 v5, v60, v1
	v_and_b32_e32 v96, 0xffff0000, v99
	v_mul_f32_e32 v5, v5, v57
	v_mul_f32_e32 v57, v61, v1
	v_mul_f32_e32 v57, v57, v96
	v_cvt_pk_bf16_f32 v57, v5, v57
	v_permlane32_swap_b32_e32 v54, v56
	s_nop 0
	v_permlane32_swap_b32_e32 v55, v57
	global_store_dwordx4 v[74:75], v[54:57], off
	v_lshlrev_b32_e32 v5, 16, v100
	v_mul_f32_e32 v59, v66, v1
	v_mul_f32_e32 v57, v62, v1
	v_and_b32_e32 v54, 0xffff0000, v100
	v_mul_f32_e32 v5, v57, v5
	v_mul_f32_e32 v57, v63, v1
	v_mul_f32_e32 v54, v57, v54
	v_lshlrev_b32_e32 v55, 16, v101
	v_cvt_pk_bf16_f32 v54, v5, v54
	v_mul_f32_e32 v5, v64, v1
	v_and_b32_e32 v56, 0xffff0000, v101
	v_mul_f32_e32 v5, v5, v55
	v_mul_f32_e32 v55, v65, v1
	v_mul_f32_e32 v55, v55, v56
	v_cvt_pk_bf16_f32 v55, v5, v55
	v_lshlrev_b32_e32 v5, 16, v94
	v_and_b32_e32 v56, 0xffff0000, v94
	v_mul_f32_e32 v5, v59, v5
	v_mul_f32_e32 v59, v67, v1
	v_mul_f32_e32 v56, v59, v56
	v_lshlrev_b32_e32 v57, 16, v95
	v_cvt_pk_bf16_f32 v56, v5, v56
	v_mul_f32_e32 v5, v68, v1
	v_and_b32_e32 v58, 0xffff0000, v95
	v_mul_f32_e32 v5, v5, v57
	v_mul_f32_e32 v57, v69, v1
	v_mul_f32_e32 v57, v57, v58
	v_cvt_pk_bf16_f32 v57, v5, v57
	v_permlane32_swap_b32_e32 v54, v56
	s_nop 0
	v_permlane32_swap_b32_e32 v55, v57
	v_lshlrev_b32_e32 v5, 16, v92
	global_store_dwordx4 v[74:75], v[54:57], off offset:32
	v_mul_f32_e32 v5, v38, v5
	v_mul_f32_e32 v38, v39, v1
	v_and_b32_e32 v54, 0xffff0000, v92
	v_mul_f32_e32 v38, v38, v54
	v_lshlrev_b32_e32 v55, 16, v93
	v_and_b32_e32 v56, 0xffff0000, v93
	v_cvt_pk_bf16_f32 v38, v5, v38
	v_mul_f32_e32 v5, v40, v1
	v_mul_f32_e32 v39, v41, v1
	v_mul_f32_e32 v5, v5, v55
	v_mul_f32_e32 v39, v39, v56
	v_cvt_pk_bf16_f32 v39, v5, v39
	v_lshlrev_b32_e32 v5, 16, v90
	v_and_b32_e32 v40, 0xffff0000, v90
	v_mul_f32_e32 v5, v42, v5
	v_mul_f32_e32 v42, v43, v1
	v_mul_f32_e32 v40, v42, v40
	v_lshlrev_b32_e32 v41, 16, v91
	v_cvt_pk_bf16_f32 v40, v5, v40
	v_mul_f32_e32 v5, v44, v1
	v_and_b32_e32 v54, 0xffff0000, v91
	v_mul_f32_e32 v5, v5, v41
	v_mul_f32_e32 v41, v45, v1
	v_mul_f32_e32 v41, v41, v54
	v_cvt_pk_bf16_f32 v41, v5, v41
	v_permlane32_swap_b32_e32 v38, v40
	s_nop 0
	v_permlane32_swap_b32_e32 v39, v41
	global_store_dwordx4 v[74:75], v[38:41], off offset:64
	v_lshlrev_b32_e32 v5, 16, v88
	v_mul_f32_e32 v43, v50, v1
	v_mul_f32_e32 v41, v46, v1
	v_and_b32_e32 v38, 0xffff0000, v88
	v_mul_f32_e32 v5, v41, v5
	v_mul_f32_e32 v41, v47, v1
	v_mul_f32_e32 v38, v41, v38
	v_lshlrev_b32_e32 v39, 16, v89
	v_cvt_pk_bf16_f32 v38, v5, v38
	v_mul_f32_e32 v5, v48, v1
	v_and_b32_e32 v40, 0xffff0000, v89
	v_mul_f32_e32 v5, v5, v39
	v_mul_f32_e32 v39, v49, v1
	v_mul_f32_e32 v39, v39, v40
	v_cvt_pk_bf16_f32 v39, v5, v39
	v_lshlrev_b32_e32 v5, 16, v86
	v_and_b32_e32 v40, 0xffff0000, v86
	v_mul_f32_e32 v5, v43, v5
	v_mul_f32_e32 v43, v51, v1
	v_mul_f32_e32 v40, v43, v40
	v_lshlrev_b32_e32 v41, 16, v87
	v_cvt_pk_bf16_f32 v40, v5, v40
	v_mul_f32_e32 v5, v52, v1
	v_and_b32_e32 v42, 0xffff0000, v87
	v_mul_f32_e32 v5, v5, v41
	v_mul_f32_e32 v41, v53, v1
	v_mul_f32_e32 v41, v41, v42
	v_cvt_pk_bf16_f32 v41, v5, v41
	v_permlane32_swap_b32_e32 v38, v40
	s_nop 0
	v_permlane32_swap_b32_e32 v39, v41
	v_lshlrev_b32_e32 v5, 16, v84
	global_store_dwordx4 v[74:75], v[38:41], off offset:96
	v_mul_f32_e32 v5, v22, v5
	v_mul_f32_e32 v22, v23, v1
	v_and_b32_e32 v38, 0xffff0000, v84
	v_mul_f32_e32 v22, v22, v38
	v_lshlrev_b32_e32 v39, 16, v85
	v_and_b32_e32 v40, 0xffff0000, v85
	v_cvt_pk_bf16_f32 v22, v5, v22
	v_mul_f32_e32 v5, v24, v1
	v_mul_f32_e32 v23, v25, v1
	v_mul_f32_e32 v5, v5, v39
	v_mul_f32_e32 v23, v23, v40
	v_cvt_pk_bf16_f32 v23, v5, v23
	v_lshlrev_b32_e32 v5, 16, v82
	v_and_b32_e32 v24, 0xffff0000, v82
	v_mul_f32_e32 v5, v26, v5
	v_mul_f32_e32 v26, v27, v1
	v_mul_f32_e32 v24, v26, v24
	v_lshlrev_b32_e32 v25, 16, v83
	v_cvt_pk_bf16_f32 v24, v5, v24
	v_mul_f32_e32 v5, v28, v1
	v_and_b32_e32 v38, 0xffff0000, v83
	v_mul_f32_e32 v5, v5, v25
	v_mul_f32_e32 v25, v29, v1
	v_mul_f32_e32 v25, v25, v38
	v_cvt_pk_bf16_f32 v25, v5, v25
	v_permlane32_swap_b32_e32 v22, v24
	s_nop 0
	v_permlane32_swap_b32_e32 v23, v25
	global_store_dwordx4 v[74:75], v[22:25], off offset:128
	v_lshlrev_b32_e32 v5, 16, v80
	v_mul_f32_e32 v27, v34, v1
	v_mul_f32_e32 v25, v30, v1
	v_and_b32_e32 v22, 0xffff0000, v80
	v_mul_f32_e32 v5, v25, v5
	v_mul_f32_e32 v25, v31, v1
	v_mul_f32_e32 v22, v25, v22
	v_lshlrev_b32_e32 v23, 16, v81
	v_cvt_pk_bf16_f32 v22, v5, v22
	v_mul_f32_e32 v5, v32, v1
	v_and_b32_e32 v24, 0xffff0000, v81
	v_mul_f32_e32 v5, v5, v23
	v_mul_f32_e32 v23, v33, v1
	v_mul_f32_e32 v23, v23, v24
	v_cvt_pk_bf16_f32 v23, v5, v23
	v_lshlrev_b32_e32 v5, 16, v78
	v_and_b32_e32 v24, 0xffff0000, v78
	v_mul_f32_e32 v5, v27, v5
	v_mul_f32_e32 v27, v35, v1
	v_mul_f32_e32 v24, v27, v24
	v_lshlrev_b32_e32 v25, 16, v79
	v_cvt_pk_bf16_f32 v24, v5, v24
	v_mul_f32_e32 v5, v36, v1
	v_and_b32_e32 v26, 0xffff0000, v79
	v_mul_f32_e32 v5, v5, v25
	v_mul_f32_e32 v25, v37, v1
	v_mul_f32_e32 v25, v25, v26
	v_cvt_pk_bf16_f32 v25, v5, v25
	v_permlane32_swap_b32_e32 v22, v24
	s_nop 0
	v_permlane32_swap_b32_e32 v23, v25
	v_lshlrev_b32_e32 v5, 16, v76
	global_store_dwordx4 v[74:75], v[22:25], off offset:160
	v_mul_f32_e32 v5, v6, v5
	v_mul_f32_e32 v6, v7, v1
	v_and_b32_e32 v22, 0xffff0000, v76
	v_mul_f32_e32 v6, v6, v22
	v_lshlrev_b32_e32 v23, 16, v77
	v_and_b32_e32 v24, 0xffff0000, v77
	v_cvt_pk_bf16_f32 v6, v5, v6
	v_mul_f32_e32 v5, v8, v1
	v_mul_f32_e32 v7, v9, v1
	v_mul_f32_e32 v5, v5, v23
	v_mul_f32_e32 v7, v7, v24
	v_cvt_pk_bf16_f32 v7, v5, v7
	v_lshlrev_b32_e32 v5, 16, v72
	v_and_b32_e32 v8, 0xffff0000, v72
	v_mul_f32_e32 v5, v10, v5
	v_mul_f32_e32 v10, v11, v1
	v_mul_f32_e32 v8, v10, v8
	v_lshlrev_b32_e32 v9, 16, v73
	v_cvt_pk_bf16_f32 v8, v5, v8
	v_mul_f32_e32 v5, v12, v1
	v_and_b32_e32 v22, 0xffff0000, v73
	v_mul_f32_e32 v5, v5, v9
	v_mul_f32_e32 v9, v13, v1
	v_mul_f32_e32 v9, v9, v22
	v_cvt_pk_bf16_f32 v9, v5, v9
	v_permlane32_swap_b32_e32 v6, v8
	s_nop 0
	v_permlane32_swap_b32_e32 v7, v9
	global_store_dwordx4 v[74:75], v[6:9], off offset:192
	v_lshlrev_b32_e32 v5, 16, v70
	s_nop 0
	v_mul_f32_e32 v9, v14, v1
	v_and_b32_e32 v6, 0xffff0000, v70
	v_mul_f32_e32 v5, v9, v5
	v_mul_f32_e32 v9, v15, v1
	v_mul_f32_e32 v6, v9, v6
	v_lshlrev_b32_e32 v7, 16, v71
	v_cvt_pk_bf16_f32 v6, v5, v6
	v_mul_f32_e32 v5, v16, v1
	v_and_b32_e32 v8, 0xffff0000, v71
	v_mul_f32_e32 v5, v5, v7
	v_mul_f32_e32 v7, v17, v1
	v_mul_f32_e32 v7, v7, v8
	v_cvt_pk_bf16_f32 v7, v5, v7
	v_lshlrev_b32_e32 v5, 16, v2
	v_mul_f32_e32 v8, v18, v1
	v_and_b32_e32 v2, 0xffff0000, v2
	v_mul_f32_e32 v5, v8, v5
	v_mul_f32_e32 v8, v19, v1
	v_mul_f32_e32 v2, v8, v2
	v_lshlrev_b32_e32 v9, 16, v3
	v_and_b32_e32 v3, 0xffff0000, v3
	v_cvt_pk_bf16_f32 v8, v5, v2
	v_mul_f32_e32 v2, v20, v1
	v_mul_f32_e32 v1, v21, v1
	v_mul_f32_e32 v2, v2, v9
	v_mul_f32_e32 v1, v1, v3
	v_cvt_pk_bf16_f32 v9, v2, v1
	v_permlane32_swap_b32_e32 v6, v8
	v_permlane32_swap_b32_e32 v7, v9
	global_store_dwordx4 v[74:75], v[6:9], off offset:224
	s_waitcnt lgkmcnt(0)
	s_barrier
	s_cbranch_vccnz .LBB0_688
